# opt28: opt26 + tile sb+2's K/V LDS-DMA pairs also issued between tile a and tile b (all eight pieces at .LBB0_903)
# baseline (speedup 1.0000x reference)
; template <bool SWA>
; __device__ __forceinline__ void unit(LAS unsigned char* lds, const bf16_t* PROJ, const bf16_t* KT, const bf16_t* VT, bf16_t* OB, int opitch, int ocol, int b, int head, int qb, float slope2, float m_init, float lam, const float* subg) {
;     ...
;         if (acta) { SM_T(s0, s1, kva, clsa); if (pvalid) PV_TILE(sa); }
;         if (actb) { SM_T(u0, u1, kvb, clsb); if (pvalid) PV_TILE(sb); }
.LBB0_903:
	s_mov_b32 m0, s32
	s_nop 0
	global_load_lds_dwordx4 v164, s[98:99]
	s_add_i32 m0, s32, 0x400
	s_nop 0
	global_load_lds_dwordx4 v170, s[98:99]
	s_mov_b32 m0, s71
	s_nop 0
	global_load_lds_dwordx4 v168, s[100:101]
	s_add_i32 m0, s71, 0x400
	s_nop 0
	global_load_lds_dwordx4 v172, s[100:101]
	s_add_i32 s29, s1, -3
	s_add_i32 s30, s1, -1
	s_cmp_lt_u32 s29, s0
	s_cselect_b32 s30, s29, s30
	s_lshl_b32 s30, s30, 14
	s_add_i32 s31, s25, 0xffffc000
	s_and_b32 s31, s31, 0x8000
	s_add_u32 s98, s73, s30
	s_addc_u32 s99, s17, 0
	s_add_i32 s92, s31, s33
	s_mov_b32 m0, s92
	s_nop 0
	global_load_lds_dwordx4 v164, s[98:99]
	s_add_i32 m0, s92, 0x400
	s_nop 0
	global_load_lds_dwordx4 v170, s[98:99]
	s_add_u32 s98, s2, s30
	s_addc_u32 s99, s23, 0
	s_add_i32 s92, s31, s72
	s_mov_b32 m0, s92
	s_nop 0
	global_load_lds_dwordx4 v168, s[98:99]
	s_add_i32 m0, s92, 0x400
	s_nop 0
	global_load_lds_dwordx4 v172, s[98:99]
	v_or_b32_e32 v96, s28, v187
	v_sub_u32_e32 v96, v188, v96
	v_cvt_f32_i32_e32 v96, v96
	s_mov_b64 s[6:7], -1
	s_and_b64 vcc, exec, s[80:81]
	s_cbranch_vccz .LBB0_909
	s_andn2_b64 vcc, exec, s[78:79]
	s_cbranch_vccnz .LBB0_906
	v_mul_f32_e64 v97, -s76, v96
	v_fma_f32 v98, -s76, v96, v194
	s_mov_b64 s[6:7], 0
